# speedup vs baseline: 1.0047x; 1.0047x over previous
; template <int EPI>
; __device__ __forceinline__ void gemm_phase(int zz, const u16* __restrict__ Wt, const u16* __restrict__ Act, int K, int lda, int nColTiles,
;                            u16* __restrict__ Out, int ldo, int nvalid, char* shm) {
;     ...
;     for (int n = 0; n < 4; ++n) {
;       int token = t0 + wc * 64 + n * 16 + fr;
;       if (EPI == 0) {
;         int col0 = c0 + wr * 128 + fq * 32;
;         if (col0 < nvalid) {
;           u16* dst = Out + (long)token * ldo + col0;
; #pragma unroll
;           for (int mm = 0; mm < 4; ++mm) {
;             uint4 v;
;             v.x = pack2(acc[2 * mm][n][0], acc[2 * mm][n][1]);
;             v.y = pack2(acc[2 * mm][n][2], acc[2 * mm][n][3]);
;             v.z = pack2(acc[2 * mm + 1][n][0], acc[2 * mm + 1][n][1]);
;             v.w = pack2(acc[2 * mm + 1][n][2], acc[2 * mm + 1][n][3]);
;             *(uint4*)(dst + mm * 8) = v;
;           }
.LBB0_258:
	s_mov_b32 s45, 1
	s_lshl_b32 s5, s43, 11
	s_or_b32 s5, s76, s5
	v_and_b32_e32 v160, 0x60, v150
	v_lshrrev_b32_e32 v161, 2, v160
	v_sub_u32_e32 v160, v161, v160
	v_add_u32_e32 v138, v138, v160
	v_ashrrev_i32_e32 v139, 31, v138
	v_or_b32_e32 v0, s5, v151
	v_lshl_add_u64 v[138:139], v[138:139], 1, s[0:1]
	v_mad_i64_i32 v[152:153], s[8:9], v0, s28, 0
	v_lshl_add_u64 v[152:153], v[152:153], 1, v[138:139]
	v_or_b32_e32 v162, 16, v0
	v_mad_i64_i32 v[154:155], s[8:9], v162, s28, 0
	v_lshl_add_u64 v[154:155], v[154:155], 1, v[138:139]
	v_or_b32_e32 v162, 32, v0
	v_mad_i64_i32 v[156:157], s[8:9], v162, s28, 0
	v_lshl_add_u64 v[156:157], v[156:157], 1, v[138:139]
	v_or_b32_e32 v162, 48, v0
	v_mad_i64_i32 v[158:159], s[8:9], v162, s28, 0
	v_lshl_add_u64 v[158:159], v[158:159], 1, v[138:139]
	v_cvt_pk_bf16_f32 v98, v98, v99
	v_cvt_pk_bf16_f32 v99, v100, v101
	v_cvt_pk_bf16_f32 v100, v102, v103
	v_cvt_pk_bf16_f32 v101, v104, v105
	v_cvt_pk_bf16_f32 v106, v106, v107
	v_cvt_pk_bf16_f32 v107, v108, v109
	v_cvt_pk_bf16_f32 v108, v110, v111
	v_cvt_pk_bf16_f32 v109, v112, v113
	v_cvt_pk_bf16_f32 v114, v114, v115
	v_cvt_pk_bf16_f32 v115, v116, v117
	v_cvt_pk_bf16_f32 v116, v122, v123
	v_cvt_pk_bf16_f32 v117, v124, v125
	v_cvt_pk_bf16_f32 v118, v118, v119
	v_cvt_pk_bf16_f32 v119, v120, v121
	v_cvt_pk_bf16_f32 v120, v126, v127
	v_cvt_pk_bf16_f32 v121, v128, v129
	s_nop 1
	v_permlane32_swap_b32_e32 v98, v114
	v_permlane32_swap_b32_e32 v99, v115
	v_permlane32_swap_b32_e32 v100, v116
	v_permlane32_swap_b32_e32 v101, v117
	v_permlane32_swap_b32_e32 v106, v118
	v_permlane32_swap_b32_e32 v107, v119
	v_permlane32_swap_b32_e32 v108, v120
	v_permlane32_swap_b32_e32 v109, v121
	v_permlane16_swap_b32_e32 v98, v106
	v_permlane16_swap_b32_e32 v99, v107
	v_permlane16_swap_b32_e32 v100, v108
	v_permlane16_swap_b32_e32 v101, v109
	v_permlane16_swap_b32_e32 v114, v118
	v_permlane16_swap_b32_e32 v115, v119
	v_permlane16_swap_b32_e32 v116, v120
	v_permlane16_swap_b32_e32 v117, v121
	s_nop 1
	s_cmpk_eq_i32 s28, 0x1680
	s_cbranch_scc1 .Lst_nt_0
	global_store_dwordx4 v[152:153], v[98:101], off
	global_store_dwordx4 v[152:153], v[106:109], off offset:64
	global_store_dwordx4 v[152:153], v[114:117], off offset:128
	global_store_dwordx4 v[152:153], v[118:121], off offset:192
	s_branch .Lst_done_0
.Lst_nt_0:
	global_store_dwordx4 v[152:153], v[98:101], off nt
	global_store_dwordx4 v[152:153], v[106:109], off offset:64 nt
	global_store_dwordx4 v[152:153], v[114:117], off offset:128 nt
	global_store_dwordx4 v[152:153], v[118:121], off offset:192 nt
.Lst_done_0:
	v_cvt_pk_bf16_f32 v66, v66, v67
	v_cvt_pk_bf16_f32 v67, v68, v69
	v_cvt_pk_bf16_f32 v68, v70, v71
	v_cvt_pk_bf16_f32 v69, v72, v73
	v_cvt_pk_bf16_f32 v74, v74, v75
	v_cvt_pk_bf16_f32 v75, v76, v77
	v_cvt_pk_bf16_f32 v76, v78, v79
	v_cvt_pk_bf16_f32 v77, v80, v81
	v_cvt_pk_bf16_f32 v82, v82, v83
	v_cvt_pk_bf16_f32 v83, v84, v85
	v_cvt_pk_bf16_f32 v84, v90, v91
	v_cvt_pk_bf16_f32 v85, v92, v93
	v_cvt_pk_bf16_f32 v86, v86, v87
	v_cvt_pk_bf16_f32 v87, v88, v89
	v_cvt_pk_bf16_f32 v88, v94, v95
	v_cvt_pk_bf16_f32 v89, v96, v97
	s_nop 1
	v_permlane32_swap_b32_e32 v66, v82
	v_permlane32_swap_b32_e32 v67, v83
	v_permlane32_swap_b32_e32 v68, v84
	v_permlane32_swap_b32_e32 v69, v85
	v_permlane32_swap_b32_e32 v74, v86
	v_permlane32_swap_b32_e32 v75, v87
	v_permlane32_swap_b32_e32 v76, v88
	v_permlane32_swap_b32_e32 v77, v89
	v_permlane16_swap_b32_e32 v66, v74
	v_permlane16_swap_b32_e32 v67, v75
	v_permlane16_swap_b32_e32 v68, v76
	v_permlane16_swap_b32_e32 v69, v77
	v_permlane16_swap_b32_e32 v82, v86
	v_permlane16_swap_b32_e32 v83, v87
	v_permlane16_swap_b32_e32 v84, v88
	v_permlane16_swap_b32_e32 v85, v89
	s_nop 1
	s_cmpk_eq_i32 s28, 0x1680
	s_cbranch_scc1 .Lst_nt_1
	global_store_dwordx4 v[154:155], v[66:69], off
	global_store_dwordx4 v[154:155], v[74:77], off offset:64
	global_store_dwordx4 v[154:155], v[82:85], off offset:128
	global_store_dwordx4 v[154:155], v[86:89], off offset:192
	s_branch .Lst_done_1
; template <int EPI>
; __device__ __forceinline__ void gemm_phase(int zz, const u16* __restrict__ Wt, const u16* __restrict__ Act, int K, int lda, int nColTiles,
;                            u16* __restrict__ Out, int ldo, int nvalid, char* shm) {
;     ...
;   for (; tile < ntiles; tile += gridDim.x) {
;     ...
;     for (int n = 0; n < 4; ++n) {
;       int token = t0 + wc * 64 + n * 16 + fr;
;       if (EPI == 0) {
;         int col0 = c0 + wr * 128 + fq * 32;
;         if (col0 < nvalid) {
;           u16* dst = Out + (long)token * ldo + col0;
; #pragma unroll
;           for (int mm = 0; mm < 4; ++mm) {
;             uint4 v;
;             v.x = pack2(acc[2 * mm][n][0], acc[2 * mm][n][1]);
;             v.y = pack2(acc[2 * mm][n][2], acc[2 * mm][n][3]);
;             v.z = pack2(acc[2 * mm + 1][n][0], acc[2 * mm + 1][n][1]);
;             v.w = pack2(acc[2 * mm + 1][n][2], acc[2 * mm + 1][n][3]);
;             *(uint4*)(dst + mm * 8) = v;
;           }
.Lst_nt_1:
	global_store_dwordx4 v[154:155], v[66:69], off nt
	global_store_dwordx4 v[154:155], v[74:77], off offset:64 nt
	global_store_dwordx4 v[154:155], v[82:85], off offset:128 nt
	global_store_dwordx4 v[154:155], v[86:89], off offset:192 nt
.Lst_done_1:
	v_cvt_pk_bf16_f32 v34, v34, v35
	v_cvt_pk_bf16_f32 v35, v36, v37
	v_cvt_pk_bf16_f32 v36, v38, v39
	v_cvt_pk_bf16_f32 v37, v40, v41
	v_cvt_pk_bf16_f32 v42, v42, v43
	v_cvt_pk_bf16_f32 v43, v44, v45
	v_cvt_pk_bf16_f32 v44, v46, v47
	v_cvt_pk_bf16_f32 v45, v48, v49
	v_cvt_pk_bf16_f32 v50, v50, v51
	v_cvt_pk_bf16_f32 v51, v52, v53
	v_cvt_pk_bf16_f32 v52, v58, v59
	v_cvt_pk_bf16_f32 v53, v60, v61
	v_cvt_pk_bf16_f32 v54, v54, v55
	v_cvt_pk_bf16_f32 v55, v56, v57
	v_cvt_pk_bf16_f32 v56, v62, v63
	v_cvt_pk_bf16_f32 v57, v64, v65
	s_nop 1
	v_permlane32_swap_b32_e32 v34, v50
	v_permlane32_swap_b32_e32 v35, v51
	v_permlane32_swap_b32_e32 v36, v52
	v_permlane32_swap_b32_e32 v37, v53
	v_permlane32_swap_b32_e32 v42, v54
	v_permlane32_swap_b32_e32 v43, v55
	v_permlane32_swap_b32_e32 v44, v56
	v_permlane32_swap_b32_e32 v45, v57
	v_permlane16_swap_b32_e32 v34, v42
	v_permlane16_swap_b32_e32 v35, v43
	v_permlane16_swap_b32_e32 v36, v44
	v_permlane16_swap_b32_e32 v37, v45
	v_permlane16_swap_b32_e32 v50, v54
	v_permlane16_swap_b32_e32 v51, v55
	v_permlane16_swap_b32_e32 v52, v56
	v_permlane16_swap_b32_e32 v53, v57
	s_nop 1
	s_cmpk_eq_i32 s28, 0x1680
	s_cbranch_scc1 .Lst_nt_2
	global_store_dwordx4 v[156:157], v[34:37], off
	global_store_dwordx4 v[156:157], v[42:45], off offset:64
	global_store_dwordx4 v[156:157], v[50:53], off offset:128
	global_store_dwordx4 v[156:157], v[54:57], off offset:192
	s_branch .Lst_done_2
.Lst_nt_2:
	global_store_dwordx4 v[156:157], v[34:37], off nt
	global_store_dwordx4 v[156:157], v[42:45], off offset:64 nt
	global_store_dwordx4 v[156:157], v[50:53], off offset:128 nt
	global_store_dwordx4 v[156:157], v[54:57], off offset:192 nt
.Lst_done_2:
	v_cvt_pk_bf16_f32 v2, v2, v3
	v_cvt_pk_bf16_f32 v3, v4, v5
	v_cvt_pk_bf16_f32 v4, v6, v7
	v_cvt_pk_bf16_f32 v5, v8, v9
	v_cvt_pk_bf16_f32 v10, v10, v11
	v_cvt_pk_bf16_f32 v11, v12, v13
	v_cvt_pk_bf16_f32 v12, v14, v15
	v_cvt_pk_bf16_f32 v13, v16, v17
	v_cvt_pk_bf16_f32 v18, v18, v19
	v_cvt_pk_bf16_f32 v19, v20, v21
	v_cvt_pk_bf16_f32 v20, v26, v27
	v_cvt_pk_bf16_f32 v21, v28, v29
	v_cvt_pk_bf16_f32 v22, v22, v23
	v_cvt_pk_bf16_f32 v23, v24, v25
	v_cvt_pk_bf16_f32 v24, v30, v31
	v_cvt_pk_bf16_f32 v25, v32, v33
	s_nop 1
	v_permlane32_swap_b32_e32 v2, v18
	v_permlane32_swap_b32_e32 v3, v19
	v_permlane32_swap_b32_e32 v4, v20
	v_permlane32_swap_b32_e32 v5, v21
	v_permlane32_swap_b32_e32 v10, v22
	v_permlane32_swap_b32_e32 v11, v23
	v_permlane32_swap_b32_e32 v12, v24
	v_permlane32_swap_b32_e32 v13, v25
	v_permlane16_swap_b32_e32 v2, v10
	v_permlane16_swap_b32_e32 v3, v11
	v_permlane16_swap_b32_e32 v4, v12
	v_permlane16_swap_b32_e32 v5, v13
	v_permlane16_swap_b32_e32 v18, v22
	v_permlane16_swap_b32_e32 v19, v23
	v_permlane16_swap_b32_e32 v20, v24
	v_permlane16_swap_b32_e32 v21, v25
	s_nop 1
	s_cmpk_eq_i32 s28, 0x1680
	s_cbranch_scc1 .Lst_nt_3
	global_store_dwordx4 v[158:159], v[2:5], off
	global_store_dwordx4 v[158:159], v[10:13], off offset:64
	global_store_dwordx4 v[158:159], v[18:21], off offset:128
	global_store_dwordx4 v[158:159], v[22:25], off offset:192
	s_branch .Lst_done_3
.Lst_nt_3:
	global_store_dwordx4 v[158:159], v[2:5], off nt
	global_store_dwordx4 v[158:159], v[10:13], off offset:64 nt
	global_store_dwordx4 v[158:159], v[18:21], off offset:128 nt
	global_store_dwordx4 v[158:159], v[22:25], off offset:192 nt
.Lst_done_3:
	s_branch .LBB0_252
.LBB0_259:
	v_readlane_b32 s16, v252, 2
	v_readlane_b32 s20, v252, 6
	v_readlane_b32 s18, v252, 4
	v_readlane_b32 s19, v252, 5
	s_mov_b32 s77, s79
	s_mov_b32 s20, s80
	v_readlane_b32 s17, v252, 3
	v_readlane_b32 s21, v252, 7
	v_readlane_b32 s22, v252, 8
	v_readlane_b32 s23, v252, 9
